# static s_setprio 1 for waves 4-7 (younger half) during the GEMM phases, reset to 0 at every phase start
# baseline (speedup 1.0000x reference)
.LBB0_3:
	s_or_b64 exec, exec, s[2:3]
	s_add_u32 s20, s56, 0x100000
	s_addc_u32 s21, s57, 0
	s_add_u32 s34, s56, 0x400000
	s_addc_u32 s35, s57, 0
	s_add_u32 s68, s56, 0x800000
	s_addc_u32 s69, s57, 0
	s_add_u32 s60, s56, 0x6000000
	s_addc_u32 s61, s57, 0
	s_lshr_b32 s80, s4, 6
	s_setprio 0
	s_cmp_lt_i32 s58, 1
	s_cselect_b64 s[2:3], -1, 0
	s_cmp_gt_i32 s59, 0
	s_cselect_b64 s[4:5], -1, 0
	s_and_b64 s[24:25], s[2:3], s[4:5]
	v_and_b32_e32 v224, 63, v196
	s_andn2_b64 vcc, exec, s[24:25]
	s_mov_b32 s81, 0
	s_waitcnt lgkmcnt(0)
	s_barrier
	s_cbranch_vccnz .LBB0_136
	s_load_dwordx16 s[4:19], s[0:1], 0x0
	s_lshl_b32 s2, s33, 3
	s_add_i32 s26, s2, s80
	s_lshl_b32 s70, s31, 3
	s_cmpk_gt_i32 s26, 0x51ff
	s_cbranch_scc1 .LBB0_78
	v_lshlrev_b32_e32 v2, 3, v196
	s_load_dwordx16 s[36:51], s[0:1], 0x40
	v_mov_b32_e32 v43, 0
	v_and_b32_e32 v46, 56, v2
	s_lshl_b32 s0, s80, 14
	v_lshlrev_b32_e32 v2, 1, v46
	v_mov_b32_e32 v3, v43
	s_add_i32 s2, s0, 0
	v_lshl_add_u64 v[2:3], s[56:57], 0, v[2:3]
	s_mov_b64 s[0:1], 0x5800000
	v_lshlrev_b32_e32 v1, 2, v196
	v_lshl_add_u64 v[48:49], v[2:3], 0, s[0:1]
	s_waitcnt lgkmcnt(0)
	s_add_u32 s28, s14, 0x1000
	s_mov_b64 s[0:1], 0x5600000
	v_and_b32_e32 v40, 28, v1
	s_addc_u32 s29, s15, 0
	v_lshl_add_u64 v[52:53], v[2:3], 0, s[0:1]
	s_mov_b64 s[0:1], 0x5200000
	v_lshrrev_b32_e32 v38, 3, v224
	v_lshlrev_b32_e32 v42, 2, v40
	s_cmp_lg_u64 s[44:45], 0
	v_lshl_add_u64 v[56:57], v[2:3], 0, s[0:1]
	s_mov_b64 s[0:1], 0x5000000
	v_add_u32_e32 v1, s2, v42
	v_mul_u32_u24_e32 v4, 0x84, v38
	v_lshl_add_u64 v[54:55], s[46:47], 0, v[42:43]
	s_cselect_b64 s[46:47], -1, 0
	v_lshl_add_u64 v[60:61], v[2:3], 0, s[0:1]
	s_cmp_lg_u64 s[14:15], 0
	s_mov_b64 s[0:1], 0x4a00000
	v_mul_u32_u24_e32 v5, 0x84, v46
	v_lshlrev_b32_e32 v6, 2, v38
	v_or_b32_e32 v74, 32, v38
	v_lshl_add_u64 v[62:63], s[40:41], 0, v[42:43]
	s_cselect_b64 s[40:41], -1, 0
	v_lshl_add_u64 v[64:65], v[2:3], 0, s[0:1]
	s_lshl_b32 s0, s26, 1
	v_add_u32_e32 v79, v1, v4
	s_mov_b32 s3, 0
	v_lshl_add_u64 v[44:45], s[50:51], 0, v[42:43]
	v_or_b32_e32 v41, 8, v38
	v_or_b32_e32 v47, 16, v38
	v_or_b32_e32 v72, 24, v38
	v_add3_u32 v73, s2, v5, v6
	v_lshl_add_u64 v[50:51], s[48:49], 0, v[42:43]
	v_mul_u32_u24_e32 v75, 0x84, v74
	v_or_b32_e32 v76, 40, v38
	v_or_b32_e32 v77, 48, v38
	v_or_b32_e32 v78, 56, v38
	v_lshl_add_u64 v[58:59], s[42:43], 0, v[42:43]
	v_mov_b32_e32 v39, v43
	s_add_i32 s27, s0, 0x7fff6000
	s_lshl_b32 s71, s70, 1
	s_lshl_b32 s72, s26, 5
	s_lshl_b32 s73, s70, 5
	v_add_u32_e32 v80, 0x420, v79
	v_add_u32_e32 v81, 0x428, v79
	v_add_u32_e32 v82, 0x840, v79
	v_add_u32_e32 v83, 0x848, v79
	v_add_u32_e32 v84, 0xc60, v79
	v_add_u32_e32 v85, 0xc68, v79
	v_add_u32_e32 v86, 0x1080, v79
	v_add_u32_e32 v87, 0x1088, v79
	v_add_u32_e32 v88, 0x14a0, v79
	v_add_u32_e32 v89, 0x14a8, v79
	s_movk_i32 s74, 0x7fff
	s_mov_b32 s75, 0xffff0000
	s_movk_i32 s76, 0x3000
	s_mov_b32 s77, 0x18000
	s_mov_b32 s78, 0x30000
	s_mov_b32 s79, 0x48000
	s_mov_b32 s82, 0x60000
	s_mov_b64 s[42:43], 0xb00000
	s_mov_b32 s83, 0x16000
	s_mov_b32 s84, 0x2c000
	s_mov_b32 s85, 0x42000
	s_mov_b32 s86, 0x58000
	v_add_u32_e32 v90, 0x18c0, v79
	v_add_u32_e32 v91, 0x18c8, v79
	v_add_u32_e32 v92, 0x1ce0, v79
	v_add_u32_e32 v93, 0x1ce8, v79
	s_mov_b32 s87, s26
	s_branch .LBB0_8

.LBB0_151:
	s_setprio 0
	s_cmp_lt_i32 s58, 2
	s_cselect_b64 s[2:3], -1, 0
	s_add_u32 s36, s56, 0xa000000
	s_addc_u32 s37, s57, 0
	s_and_b64 s[2:3], s[2:3], s[0:1]
	s_andn2_b64 vcc, exec, s[2:3]
	s_cbranch_vccnz .LBB0_168
	s_cmpk_gt_i32 s30, 0xaff
	v_readfirstlane_b32 s1, v196
	s_cbranch_scc1 .LBB0_168
	v_lshrrev_b32_e32 v2, 1, v196
	v_lshrrev_b32_e32 v3, 5, v196
	v_and_b32_e32 v2, 24, v2
	v_and_b32_e32 v3, 4, v3
	v_bfe_u32 v4, v196, 2, 2
	v_lshlrev_b32_e32 v0, 4, v196
	v_and_b32_e32 v1, 32, v196
	v_bfe_u32 v10, v196, 2, 4
	v_or3_b32 v2, v3, v4, v2
	v_lshrrev_b32_e32 v3, 3, v196
	s_movk_i32 s0, 0x70
	v_bitop3_b32 v8, v0, v1, 48 bitop3:0x6c
	v_and_b32_e32 v9, 64, v196
	v_and_or_b32 v4, v3, s0, v10
	s_movk_i32 s0, 0x60
	v_add_u32_e32 v11, 0x2000, v0
	v_or_b32_e32 v1, v8, v9
	v_and_or_b32 v3, v3, s0, v2
	v_lshrrev_b32_e32 v0, 7, v11
	s_movk_i32 s0, 0xf0
	v_lshl_or_b32 v130, v3, 11, v1
	v_and_or_b32 v3, v0, s0, v10
	s_movk_i32 s0, 0xe0
	s_ashr_i32 s29, s30, 31
	v_and_or_b32 v0, v0, s0, v2
	s_lshr_b32 s0, s29, 29
	s_add_i32 s0, s30, s0
	s_waitcnt lgkmcnt(0)
	s_lshr_b32 s6, s1, 6
	s_ashr_i32 s4, s0, 3
	s_and_b32 s0, s0, -8
	s_lshr_b32 s8, s1, 8
	s_lshl_b32 s28, s6, 10
	s_sub_i32 s0, s30, s0
	s_cmp_lt_i32 s0, 0
	s_movk_i32 s38, 0x161
	s_cselect_b32 s5, s38, 0x160
	s_mul_i32 s0, s0, s5
	s_add_i32 s0, s0, s4
	s_mul_hi_i32 s4, s0, 0x2e8ba2e9
	s_lshr_b32 s5, s4, 31
	s_ashr_i32 s4, s4, 5
	s_add_i32 s4, s4, s5
	s_lshl_b32 s5, s4, 3
	s_mulk_i32 s4, 0xb0
	s_sub_i32 s4, s0, s4
	s_sext_i32_i16 s0, s4
	s_bfe_u32 s0, s0, 0x3001c
	s_add_i32 s7, s4, s0
	s_sext_i32_i16 s0, s7
	s_and_b32 s7, s7, 0xfff8
	s_sub_i32 s4, s4, s7
	s_sext_i32_i16 s4, s4
	s_lshr_b32 s0, s0, 3
	s_add_i32 s18, s5, s4
	s_ashr_i32 s19, s18, 31
	s_bfe_i64 s[10:11], s[0:1], 0x100000
	s_lshl_b64 s[4:5], s[18:19], 19
	s_lshl_b64 s[10:11], s[10:11], 19
	s_add_u32 s24, s68, s10
	s_addc_u32 s25, s69, s11
	s_add_i32 s19, s28, 0
	s_add_i32 m0, s19, 0x10000
	v_lshl_or_b32 v134, v0, 11, v1
	global_load_lds_dwordx4 v130, s[24:25]
	s_add_i32 m0, s19, 0x12000
	s_add_u32 s10, s24, 0x40000
	global_load_lds_dwordx4 v134, s[24:25]
	s_addc_u32 s11, s25, 0
	s_add_i32 m0, s19, 0x14000
	v_lshl_or_b32 v128, v4, 11, v1
	global_load_lds_dwordx4 v130, s[10:11]
	s_add_i32 m0, s19, 0x16000
	s_add_u32 s22, s60, s4
	s_addc_u32 s23, s61, s5
	s_add_i32 s39, s19, 0x2000
	global_load_lds_dwordx4 v134, s[10:11]
	s_mov_b32 m0, s19
	s_add_u32 s4, s22, 0x40000
	v_lshl_or_b32 v132, v3, 11, v1
	global_load_lds_dwordx4 v128, s[22:23]
	s_mov_b32 m0, s39
	s_addc_u32 s5, s23, 0
	s_add_i32 s40, s19, 0x4000
	global_load_lds_dwordx4 v132, s[22:23]
	s_mov_b32 m0, s40
	s_add_i32 s41, s19, 0x6000
	global_load_lds_dwordx4 v128, s[4:5]
	s_mov_b32 m0, s41
	v_mov_b32_e32 v131, 0
	global_load_lds_dwordx4 v132, s[4:5]
	v_mov_b32_e32 v135, v131
	v_mov_b32_e32 v129, v131
	v_mov_b32_e32 v133, v131
	s_cmp_eq_u32 s8, 1
	s_mov_b32 s42, 0
	v_lshl_add_u64 v[6:7], s[24:25], 0, v[130:131]
	v_lshl_add_u64 v[4:5], s[24:25], 0, v[134:135]
	v_lshl_add_u64 v[0:1], s[22:23], 0, v[128:129]
	s_cselect_b64 s[4:5], -1, 0
	s_cmp_lg_u32 s8, 1
	v_lshl_add_u64 v[2:3], s[22:23], 0, v[132:133]
	s_cbranch_scc1 .LBB0_155
	s_barrier
	s_setprio 1

.LBB0_218:
	s_setprio 0
	s_cmp_lt_i32 s58, 3
	s_cselect_b64 s[0:1], -1, 0
	s_and_b64 s[6:7], s[0:1], s[4:5]
	s_andn2_b64 vcc, exec, s[6:7]
	s_cbranch_vccnz .LBB0_261
	s_cmpk_lt_i32 s30, 0x200
	s_cselect_b64 s[0:1], -1, 0
	s_cmpk_gt_i32 s30, 0x1ff
	v_readfirstlane_b32 s2, v196
	s_cbranch_scc1 .LBB0_221
	s_ashr_i32 s3, s30, 31
	s_lshr_b32 s3, s3, 29
	s_add_i32 s3, s30, s3
	s_and_b32 s4, s3, -8
	s_sub_i32 s4, s30, s4
	s_lshl_b32 s8, s4, 6
	s_ashr_i32 s3, s3, 3
	s_mul_i32 s5, s4, 0x41
	s_cmp_lt_i32 s4, 0
	s_cselect_b32 s4, s5, s8
	s_add_i32 s3, s4, s3
	s_ashr_i32 s4, s3, 31
	s_lshr_b32 s4, s4, 27
	s_add_i32 s4, s3, s4
	s_ashr_i32 s5, s4, 5
	s_andn2_b32 s4, s4, 31
	s_sub_i32 s3, s3, s4
	s_bfe_i32 s4, s3, 0x80000
	s_bfe_u32 s4, s4, 0x3000c
	s_add_i32 s4, s3, s4
	s_bfe_i32 s8, s4, 0x80000
	s_and_b32 s4, s4, 0xf8
	s_sub_i32 s3, s3, s4
	s_lshl_b32 s5, s5, 3
	s_sext_i32_i16 s8, s8
	s_sext_i32_i8 s3, s3
	s_add_i32 s51, s5, s3
	s_ashr_i32 s8, s8, 3
.LBB0_221:
	s_andn2_b64 vcc, exec, s[0:1]
	s_cbranch_vccnz .LBB0_261
	v_lshrrev_b32_e32 v3, 1, v196
	v_lshrrev_b32_e32 v4, 5, v196
	v_and_b32_e32 v3, 24, v3
	v_and_b32_e32 v4, 4, v4
	v_bfe_u32 v5, v196, 2, 2
	v_lshlrev_b32_e32 v0, 4, v196
	v_and_b32_e32 v1, 32, v196
	v_bfe_u32 v2, v196, 2, 4
	v_or3_b32 v3, v4, v5, v3
	v_lshrrev_b32_e32 v4, 3, v196
	s_movk_i32 s0, 0x70
	v_bitop3_b32 v8, v0, v1, 48 bitop3:0x6c
	v_and_or_b32 v5, v4, s0, v2
	s_movk_i32 s0, 0x60
	v_add_u32_e32 v0, 0x2000, v0
	v_and_or_b32 v4, v4, s0, v3
	v_lshrrev_b32_e32 v0, 7, v0
	s_movk_i32 s0, 0xf0
	s_add_u32 s26, s56, 0x1300000
	v_and_or_b32 v2, v0, s0, v2
	s_movk_i32 s0, 0xe0
	s_addc_u32 s27, s57, 0
	v_and_b32_e32 v9, 64, v196
	v_and_or_b32 v0, v0, s0, v3
	s_lshr_b32 s0, s2, 6
	v_or_b32_e32 v1, v8, v9
	s_lshr_b32 s3, s2, 8
	s_lshl_b32 s28, s0, 10
	s_mul_i32 s5, s8, 0x160000
	v_lshrrev_b32_e32 v1, 1, v1
	v_mul_u32_u24_e32 v4, 0xb00, v4
	s_mul_hi_i32 s4, s8, 0x160000
	s_add_u32 s22, s26, s5
	v_or_b32_e32 v4, v4, v1
	s_addc_u32 s23, s27, s4
	s_add_i32 s29, s28, 0
	v_lshlrev_b32_e32 v154, 1, v4
	v_mul_u32_u24_e32 v0, 0xb00, v0
	s_add_i32 m0, s29, 0x10000
	v_or_b32_e32 v0, v0, v1
	global_load_lds_dwordx4 v154, s[22:23]
	s_add_i32 m0, s29, 0x12000
	v_lshlrev_b32_e32 v158, 1, v0
	s_add_u32 s4, s22, 0xb0000
	global_load_lds_dwordx4 v158, s[22:23]
	s_addc_u32 s5, s23, 0
	s_add_i32 m0, s29, 0x14000
	s_mul_i32 s9, s51, 0x160000
	global_load_lds_dwordx4 v154, s[4:5]
	s_add_i32 m0, s29, 0x16000
	v_mul_u32_u24_e32 v10, 0xb00, v5
	s_mul_hi_i32 s1, s51, 0x160000
	s_add_u32 s18, s36, s9
	v_or_b32_e32 v5, v1, v10
	v_mul_u32_u24_e32 v11, 0xb00, v2
	s_addc_u32 s19, s37, s1
	s_add_i32 s38, s29, 0x2000
	v_lshlrev_b32_e32 v152, 1, v5
	v_or_b32_e32 v2, v11, v1
	global_load_lds_dwordx4 v158, s[4:5]
	s_mov_b32 m0, s29
	s_add_u32 s4, s18, 0xb0000
	v_lshlrev_b32_e32 v156, 1, v2
	global_load_lds_dwordx4 v152, s[18:19]
	s_mov_b32 m0, s38
	s_addc_u32 s5, s19, 0
	s_add_i32 s39, s29, 0x4000
	global_load_lds_dwordx4 v156, s[18:19]
	s_mov_b32 m0, s39
	s_add_i32 s40, s29, 0x6000
	global_load_lds_dwordx4 v152, s[4:5]
	s_mov_b32 m0, s40
	v_mov_b32_e32 v155, 0
	global_load_lds_dwordx4 v156, s[4:5]
	v_mov_b32_e32 v159, v155
	v_mov_b32_e32 v153, v155
	v_mov_b32_e32 v157, v155
	s_cmp_eq_u32 s3, 1
	s_mov_b32 s9, 0
	v_lshl_add_u64 v[6:7], s[22:23], 0, v[154:155]
	v_lshl_add_u64 v[4:5], s[22:23], 0, v[158:159]
	v_lshl_add_u64 v[0:1], s[18:19], 0, v[152:153]
	s_cselect_b64 s[10:11], -1, 0
	s_cmp_lg_u32 s3, 1
	v_lshl_add_u64 v[2:3], s[18:19], 0, v[156:157]
	s_cbranch_scc1 .LBB0_224
	s_barrier
	s_setprio 1

.LBB0_311:
	s_setprio 0
	s_cmp_lt_i32 s58, 4
	s_cselect_b64 s[2:3], -1, 0
	s_and_b64 s[4:5], s[2:3], s[0:1]
	s_andn2_b64 vcc, exec, s[4:5]
	s_cbranch_vccnz .LBB0_608
	s_cmpk_lt_i32 s30, 0x600
	s_cselect_b64 s[0:1], -1, 0
	s_cmpk_gt_i32 s30, 0x5ff
	v_readfirstlane_b32 s12, v196
	s_cbranch_scc1 .LBB0_314
	s_ashr_i32 s2, s30, 31
	s_lshr_b32 s2, s2, 29
	s_add_i32 s2, s30, s2
	s_ashr_i32 s3, s2, 3
	s_and_b32 s2, s2, -8
	s_sub_i32 s2, s30, s2
	s_cmp_lt_i32 s2, 0
	s_movk_i32 s6, 0xc1
	s_cselect_b32 s6, s6, 0xc0
	s_mul_i32 s2, s2, s6
	s_add_i32 s2, s2, s3
	s_mul_hi_i32 s3, s2, 0x2aaaaaab
	s_lshr_b32 s6, s3, 31
	s_ashr_i32 s3, s3, 4
	s_add_i32 s3, s3, s6
	s_lshl_b32 s6, s3, 3
	s_mulk_i32 s3, 0x60
	s_sub_i32 s2, s2, s3
	s_bfe_i32 s3, s2, 0x80000
	s_bfe_u32 s3, s3, 0x3000c
	s_add_i32 s3, s2, s3
	s_bfe_i32 s7, s3, 0x80000
	s_and_b32 s3, s3, 0xf8
	s_sub_i32 s2, s2, s3
	s_sext_i32_i16 s7, s7
	s_sext_i32_i8 s2, s2
	s_add_i32 s2, s6, s2
	s_ashr_i32 s26, s7, 3
.LBB0_314:
	s_andn2_b64 vcc, exec, s[0:1]
	s_cbranch_vccnz .LBB0_608
	v_lshrrev_b32_e32 v2, 1, v196
	v_lshrrev_b32_e32 v3, 5, v196
	v_and_b32_e32 v2, 24, v2
	v_and_b32_e32 v3, 4, v3
	v_bfe_u32 v4, v196, 2, 2
	v_lshlrev_b32_e32 v0, 4, v196
	s_waitcnt lgkmcnt(0)
	v_and_b32_e32 v1, 32, v196
	v_bfe_u32 v10, v196, 2, 4
	v_or3_b32 v2, v3, v4, v2
	v_lshrrev_b32_e32 v3, 3, v196
	s_movk_i32 s0, 0x70
	v_bitop3_b32 v8, v0, v1, 48 bitop3:0x6c
	v_and_b32_e32 v9, 64, v196
	v_and_or_b32 v4, v3, s0, v10
	s_movk_i32 s0, 0x60
	v_add_u32_e32 v11, 0x2000, v0
	s_add_u32 s40, s56, 0x4a00000
	v_or_b32_e32 v1, v8, v9
	v_and_or_b32 v3, v3, s0, v2
	v_lshrrev_b32_e32 v0, 7, v11
	s_movk_i32 s0, 0xf0
	s_addc_u32 s41, s57, 0
	v_lshl_or_b32 v162, v3, 11, v1
	v_and_or_b32 v3, v0, s0, v10
	s_movk_i32 s0, 0xe0
	s_lshr_b32 s1, s12, 6
	s_ashr_i32 s3, s2, 31
	s_ashr_i32 s27, s26, 31
	v_and_or_b32 v0, v0, s0, v2
	s_lshr_b32 s0, s12, 8
	s_lshl_b32 s42, s1, 10
	s_lshl_b64 s[6:7], s[2:3], 19
	s_lshl_b64 s[8:9], s[26:27], 19
	s_add_u32 s28, s40, s8
	s_addc_u32 s29, s41, s9
	s_add_i32 s43, s42, 0
	s_add_i32 m0, s43, 0x10000
	v_lshl_or_b32 v166, v0, 11, v1
	global_load_lds_dwordx4 v162, s[28:29]
	s_add_i32 m0, s43, 0x12000
	s_add_u32 s8, s28, 0x40000
	global_load_lds_dwordx4 v166, s[28:29]
	s_addc_u32 s9, s29, 0
	s_add_i32 m0, s43, 0x14000
	v_lshl_or_b32 v160, v4, 11, v1
	global_load_lds_dwordx4 v162, s[8:9]
	s_add_i32 m0, s43, 0x16000
	s_add_u32 s24, s60, s6
	s_addc_u32 s25, s61, s7
	s_add_i32 s44, s43, 0x2000
	global_load_lds_dwordx4 v166, s[8:9]
	s_mov_b32 m0, s43
	s_add_u32 s6, s24, 0x40000
	v_lshl_or_b32 v164, v3, 11, v1
	global_load_lds_dwordx4 v160, s[24:25]
	s_mov_b32 m0, s44
	s_addc_u32 s7, s25, 0
	s_add_i32 s45, s43, 0x4000
	global_load_lds_dwordx4 v164, s[24:25]
	s_mov_b32 m0, s45
	s_add_i32 s46, s43, 0x6000
	global_load_lds_dwordx4 v160, s[6:7]
	s_mov_b32 m0, s46
	v_mov_b32_e32 v169, 0
	global_load_lds_dwordx4 v164, s[6:7]
	v_mov_b32_e32 v163, v169
	v_mov_b32_e32 v167, v169
	v_mov_b32_e32 v161, v169
	v_mov_b32_e32 v165, v169
	s_cmp_eq_u32 s0, 1
	s_mov_b32 s47, 0
	v_lshl_add_u64 v[6:7], s[28:29], 0, v[162:163]
	v_lshl_add_u64 v[4:5], s[28:29], 0, v[166:167]
	v_lshl_add_u64 v[0:1], s[24:25], 0, v[160:161]
	s_cselect_b64 s[6:7], -1, 0
	s_cmp_lg_u32 s0, 1
	v_lshl_add_u64 v[2:3], s[24:25], 0, v[164:165]
	s_cbranch_scc1 .LBB0_317
	s_barrier
	s_setprio 1

.LBB0_658:
	s_setprio 0
	s_cmp_lt_i32 s58, 5
	s_cselect_b64 s[2:3], -1, 0
	s_add_u32 s38, s56, 0xe000000
	s_addc_u32 s39, s57, 0
	s_add_u32 s40, s56, 0x15000000
	s_addc_u32 s41, s57, 0
	s_add_u32 s42, s56, 0x19000000
	s_addc_u32 s43, s57, 0
	s_and_b64 s[4:5], s[2:3], s[0:1]
	s_andn2_b64 vcc, exec, s[4:5]
	s_cbranch_vccnz .LBB0_726
	s_cmpk_gt_i32 s33, 0x3ff
	v_readfirstlane_b32 s0, v196
	s_cbranch_scc1 .LBB0_726
	v_lshrrev_b32_e32 v0, 5, v224
	v_and_b32_e32 v197, 31, v196
	v_lshlrev_b32_e32 v198, 2, v0
	v_lshlrev_b32_e32 v7, 3, v196
	v_and_b32_e32 v210, 56, v7
	v_sub_u32_e32 v7, v197, v198
	s_movk_i32 s18, 0x81
	s_lshr_b32 s19, s0, 6
	v_lshrrev_b32_e32 v199, 3, v224
	v_lshlrev_b32_e32 v2, 9, v196
	v_and_b32_e32 v4, 3, v196
	v_lshlrev_b32_e32 v6, 1, v196
	v_mov_b32_e32 v211, 0xff800000
	v_bfrev_b32_e32 v8, 1
	v_cmp_gt_u32_e32 vcc, s18, v7
	v_add_u32_e32 v9, -1, v7
	s_mul_i32 s1, s19, 0x2200
	v_and_b32_e32 v2, 0x800, v2
	v_lshlrev_b32_e32 v3, 6, v199
	v_lshlrev_b32_e32 v5, 4, v4
	v_and_b32_e32 v6, 32, v6
	v_lshlrev_b32_e32 v4, 3, v4
	v_cndmask_b32_e32 v32, v211, v8, vcc
	v_cmp_gt_u32_e32 vcc, s18, v9
	v_add_u32_e32 v9, -2, v7
	s_add_i32 s1, s1, 0
	s_abs_i32 s22, s31
	v_cndmask_b32_e32 v33, v211, v8, vcc
	v_cmp_gt_u32_e32 vcc, s18, v9
	v_add_u32_e32 v9, -3, v7
	v_add3_u32 v2, s1, v2, v3
	v_add3_u32 v3, s1, v6, v4
	v_cvt_f32_u32_e32 v6, s22
	v_cndmask_b32_e32 v34, v211, v8, vcc
	v_cmp_gt_u32_e32 vcc, s18, v9
	v_add_u32_e32 v9, -8, v7
	v_rcp_iflag_f32_e32 v6, v6
	v_cndmask_b32_e32 v35, v211, v8, vcc
	v_cmp_gt_u32_e32 vcc, s18, v9
	v_add_u32_e32 v9, -9, v7
	v_mul_f32_e32 v6, 0x4f7ffffe, v6
	s_waitcnt vmcnt(7)
	v_cndmask_b32_e32 v36, v211, v8, vcc
	v_cmp_gt_u32_e32 vcc, s18, v9
	v_add_u32_e32 v9, -10, v7
	v_cvt_u32_f32_e32 v6, v6
	v_cndmask_b32_e32 v37, v211, v8, vcc
	v_cmp_gt_u32_e32 vcc, s18, v9
	v_add_u32_e32 v9, -11, v7
	s_bfe_u32 s24, s0, 0x20006
	v_cndmask_b32_e32 v38, v211, v8, vcc
	v_cmp_gt_u32_e32 vcc, s18, v9
	v_add_u32_e32 v9, -16, v7
	s_lshr_b32 s0, s0, 8
	v_cndmask_b32_e32 v39, v211, v8, vcc
	v_cmp_gt_u32_e32 vcc, s18, v9
	v_subrev_u32_e32 v9, 17, v7
	v_lshlrev_b32_e32 v16, 4, v0
	s_waitcnt vmcnt(6)
	v_cndmask_b32_e32 v40, v211, v8, vcc
	v_cmp_gt_u32_e32 vcc, s18, v9
	v_subrev_u32_e32 v9, 18, v7
	v_lshrrev_b32_e32 v0, 2, v196
	v_cndmask_b32_e32 v41, v211, v8, vcc
	v_cmp_gt_u32_e32 vcc, s18, v9
	v_subrev_u32_e32 v9, 19, v7
	v_lshl_add_u32 v212, v197, 2, s0
	v_cndmask_b32_e32 v42, v211, v8, vcc
	v_cmp_gt_u32_e32 vcc, s18, v9
	v_subrev_u32_e32 v9, 24, v7
	s_sub_i32 s0, 0, s22
	v_cndmask_b32_e32 v43, v211, v8, vcc
	v_cmp_gt_u32_e32 vcc, s18, v9
	v_subrev_u32_e32 v9, 25, v7
	s_waitcnt lgkmcnt(0)
	v_lshlrev_b32_e32 v1, 4, v196
	s_waitcnt vmcnt(5)
	v_cndmask_b32_e32 v44, v211, v8, vcc
	v_cmp_gt_u32_e32 vcc, s18, v9
	v_subrev_u32_e32 v9, 26, v7
	v_subrev_u32_e32 v7, 27, v7
	v_cndmask_b32_e32 v45, v211, v8, vcc
	v_cmp_gt_u32_e32 vcc, s18, v9
	v_and_or_b32 v0, v0, 3, v198
	s_movk_i32 s2, 0x90
	v_cndmask_b32_e32 v46, v211, v8, vcc
	v_cmp_gt_u32_e32 vcc, s18, v7
	v_mov_b32_e32 v7, s1
	v_readfirstlane_b32 s1, v6
	s_mul_i32 s0, s0, s1
	v_and_b32_e32 v1, 0x70, v1
	v_lshlrev_b32_e32 v0, 6, v0
	v_mov_b32_e32 v17, 0
	v_cndmask_b32_e32 v47, v211, v8, vcc
	v_mad_u32_u24 v8, v199, s2, v7
	v_mad_u32_u24 v7, v197, s2, v7
	v_lshlrev_b32_e32 v4, 4, v197
	s_add_i32 s23, s19, 8
	s_mul_hi_u32 s0, s1, s0
	s_mov_b32 s7, 0
	v_lshl_add_u64 v[200:201], s[36:37], 0, v[16:17]
	v_add_u32_e32 v202, s19, v4
	v_mov_b32_e32 v203, v17
	v_add_u32_e32 v213, 2, v212
	v_add_u32_e32 v214, s23, v4
	s_ashr_i32 s25, s31, 31
	s_add_i32 s26, s1, s0
	s_mov_b64 s[8:9], 0x4000
	s_movk_i32 s27, 0x4000
	s_mov_b32 s28, 0x40c00000
	v_lshlrev_b32_e32 v204, 1, v198
	v_add_u32_e32 v215, v8, v1
	v_add_u32_e32 v216, v2, v5
	v_add_u32_e32 v217, v7, v16
	v_add_u32_e32 v218, v3, v0
	s_mov_b32 s29, s33
	s_mov_b32 s44, s33
	s_branch .LBB0_662

.LBB0_776:
	s_setprio 0
	s_cmp_lt_i32 s58, 6
	s_cselect_b64 s[2:3], -1, 0
	s_and_b64 s[4:5], s[2:3], s[0:1]
	s_andn2_b64 vcc, exec, s[4:5]
	s_cbranch_vccnz .LBB0_819
	s_cmpk_lt_i32 s30, 0x200
	s_cselect_b64 s[0:1], -1, 0
	s_cmpk_gt_i32 s30, 0x1ff
	v_readfirstlane_b32 s12, v196
	s_cbranch_scc1 .LBB0_783
	s_ashr_i32 s2, s30, 31
	s_lshr_b32 s2, s2, 29
	s_add_i32 s6, s30, s2
	s_and_b32 s2, s6, -8
	s_sub_i32 s7, s30, s2
	s_cmp_gt_i32 s7, -1
	s_cbranch_scc0 .LBB0_780
	s_lshl_b32 s8, s7, 6
	s_cbranch_execz .LBB0_781
	s_branch .LBB0_782

.LBB0_783:
	s_andn2_b64 vcc, exec, s[0:1]
	s_cbranch_vccnz .LBB0_819
	v_lshrrev_b32_e32 v2, 1, v196
	v_lshrrev_b32_e32 v3, 5, v196
	v_and_b32_e32 v2, 24, v2
	v_and_b32_e32 v3, 4, v3
	v_bfe_u32 v4, v196, 2, 2
	v_lshlrev_b32_e32 v0, 4, v196
	s_waitcnt lgkmcnt(0)
	v_and_b32_e32 v1, 32, v196
	v_bfe_u32 v10, v196, 2, 4
	v_or3_b32 v2, v3, v4, v2
	v_lshrrev_b32_e32 v3, 3, v196
	s_movk_i32 s0, 0x70
	v_bitop3_b32 v8, v0, v1, 48 bitop3:0x6c
	v_and_b32_e32 v9, 64, v196
	v_and_or_b32 v4, v3, s0, v10
	s_movk_i32 s0, 0x60
	v_add_u32_e32 v11, 0x2000, v0
	s_add_u32 s46, s56, 0x5000000
	v_or_b32_e32 v1, v8, v9
	v_and_or_b32 v3, v3, s0, v2
	v_lshrrev_b32_e32 v0, 7, v11
	s_movk_i32 s0, 0xf0
	s_addc_u32 s47, s57, 0
	s_lshr_b32 s1, s12, 6
	v_lshl_or_b32 v154, v3, 11, v1
	v_and_or_b32 v3, v0, s0, v10
	s_movk_i32 s0, 0xe0
	s_ashr_i32 s25, s24, 31
	s_ashr_i32 s7, s6, 31
	v_and_or_b32 v0, v0, s0, v2
	s_lshr_b32 s0, s12, 8
	s_lshl_b32 s48, s1, 10
	s_lshl_b64 s[2:3], s[24:25], 19
	s_lshl_b64 s[8:9], s[6:7], 19
	s_add_u32 s28, s46, s8
	s_addc_u32 s29, s47, s9
	s_add_i32 s49, s48, 0
	s_add_i32 m0, s49, 0x10000
	v_lshl_or_b32 v158, v0, 11, v1
	global_load_lds_dwordx4 v154, s[28:29]
	s_add_i32 m0, s49, 0x12000
	s_add_u32 s8, s28, 0x40000
	global_load_lds_dwordx4 v158, s[28:29]
	s_addc_u32 s9, s29, 0
	s_add_i32 m0, s49, 0x14000
	v_lshl_or_b32 v152, v4, 11, v1
	global_load_lds_dwordx4 v154, s[8:9]
	s_add_i32 m0, s49, 0x16000
	s_add_u32 s26, s38, s2
	s_addc_u32 s27, s39, s3
	s_add_i32 s50, s49, 0x2000
	global_load_lds_dwordx4 v158, s[8:9]
	s_mov_b32 m0, s49
	s_add_u32 s2, s26, 0x40000
	v_lshl_or_b32 v156, v3, 11, v1
	global_load_lds_dwordx4 v152, s[26:27]
	s_mov_b32 m0, s50
	s_addc_u32 s3, s27, 0
	s_add_i32 s51, s49, 0x4000
	global_load_lds_dwordx4 v156, s[26:27]
	s_mov_b32 m0, s51
	s_add_i32 s64, s49, 0x6000
	global_load_lds_dwordx4 v152, s[2:3]
	s_mov_b32 m0, s64
	v_mov_b32_e32 v155, 0
	global_load_lds_dwordx4 v156, s[2:3]
	v_mov_b32_e32 v159, v155
	v_mov_b32_e32 v153, v155
	v_mov_b32_e32 v157, v155
	s_cmp_eq_u32 s0, 1
	s_mov_b32 s7, 0
	v_lshl_add_u64 v[6:7], s[28:29], 0, v[154:155]
	v_lshl_add_u64 v[4:5], s[28:29], 0, v[158:159]
	v_lshl_add_u64 v[0:1], s[26:27], 0, v[152:153]
	s_cselect_b64 s[8:9], -1, 0
	s_cmp_lg_u32 s0, 1
	v_lshl_add_u64 v[2:3], s[26:27], 0, v[156:157]
	s_cbranch_scc1 .LBB0_786
	s_barrier
	s_setprio 1

.LBB0_869:
	s_setprio 0
	s_cmp_lt_i32 s58, 7
	s_cselect_b64 s[2:3], -1, 0
	s_and_b64 s[2:3], s[2:3], s[0:1]
	s_andn2_b64 vcc, exec, s[2:3]
	s_cbranch_vccnz .LBB0_886
	s_cmpk_gt_i32 s30, 0xaff
	v_readfirstlane_b32 s1, v196
	s_cbranch_scc1 .LBB0_886
	v_lshrrev_b32_e32 v0, 5, v196
	v_lshrrev_b32_e32 v2, 1, v196
	v_and_b32_e32 v0, 4, v0
	s_waitcnt lgkmcnt(0)
	v_bfe_u32 v1, v196, 2, 2
	v_and_b32_e32 v2, 24, v2
	v_or3_b32 v0, v0, v1, v2
	v_lshlrev_b32_e32 v1, 4, v196
	v_add_u32_e32 v8, 0x2000, v1
	v_lshrrev_b32_e32 v2, 7, v8
	s_movk_i32 s0, 0xe0
	v_and_b32_e32 v4, 32, v196
	v_and_or_b32 v3, v2, s0, v0
	v_bitop3_b32 v9, v1, v4, 48 bitop3:0x6c
	v_and_b32_e32 v10, 64, v196
	v_bfe_u32 v11, v196, 2, 4
	s_movk_i32 s0, 0xf0
	v_or_b32_e32 v1, v9, v10
	v_and_or_b32 v2, v2, s0, v11
	s_add_u32 s28, s56, 0x1880000
	v_lshl_or_b32 v130, v2, 11, v1
	v_lshrrev_b32_e32 v2, 3, v196
	s_movk_i32 s0, 0x60
	s_addc_u32 s29, s57, 0
	v_and_or_b32 v0, v2, s0, v0
	s_movk_i32 s0, 0x70
	s_ashr_i32 s45, s30, 31
	v_lshl_or_b32 v132, v0, 11, v1
	v_and_or_b32 v0, v2, s0, v11
	s_lshr_b32 s0, s45, 29
	s_add_i32 s0, s30, s0
	s_lshr_b32 s6, s1, 6
	s_ashr_i32 s4, s0, 3
	s_and_b32 s0, s0, -8
	s_lshr_b32 s8, s1, 8
	s_lshl_b32 s44, s6, 10
	s_sub_i32 s0, s30, s0
	s_cmp_lt_i32 s0, 0
	s_movk_i32 s46, 0x161
	s_cselect_b32 s5, s46, 0x160
	s_mul_i32 s0, s0, s5
	s_add_i32 s0, s0, s4
	s_mul_hi_i32 s4, s0, 0x2e8ba2e9
	s_lshr_b32 s5, s4, 31
	s_ashr_i32 s4, s4, 5
	s_add_i32 s4, s4, s5
	s_lshl_b32 s5, s4, 3
	s_mulk_i32 s4, 0xb0
	s_sub_i32 s4, s0, s4
	s_sext_i32_i16 s0, s4
	s_bfe_u32 s0, s0, 0x3001c
	s_add_i32 s7, s4, s0
	s_sext_i32_i16 s0, s7
	s_and_b32 s7, s7, 0xfff8
	s_sub_i32 s4, s4, s7
	s_sext_i32_i16 s4, s4
	s_lshr_b32 s0, s0, 3
	s_add_i32 s18, s5, s4
	s_ashr_i32 s19, s18, 31
	s_bfe_i64 s[10:11], s[0:1], 0x100000
	s_lshl_b64 s[4:5], s[18:19], 19
	s_lshl_b64 s[10:11], s[10:11], 19
	s_add_u32 s24, s28, s10
	s_addc_u32 s25, s29, s11
	s_add_i32 s19, s44, 0
	s_add_i32 m0, s19, 0x10000
	v_lshl_or_b32 v128, v3, 11, v1
	global_load_lds_dwordx4 v132, s[24:25]
	s_add_i32 m0, s19, 0x12000
	s_add_u32 s10, s24, 0x40000
	global_load_lds_dwordx4 v128, s[24:25]
	s_addc_u32 s11, s25, 0
	s_add_i32 m0, s19, 0x14000
	v_lshl_or_b32 v134, v0, 11, v1
	global_load_lds_dwordx4 v132, s[10:11]
	s_add_i32 m0, s19, 0x16000
	s_add_u32 s22, s60, s4
	s_addc_u32 s23, s61, s5
	s_add_i32 s47, s19, 0x2000
	global_load_lds_dwordx4 v128, s[10:11]
	s_mov_b32 m0, s19
	s_add_u32 s4, s22, 0x40000
	global_load_lds_dwordx4 v134, s[22:23]
	s_mov_b32 m0, s47
	s_addc_u32 s5, s23, 0
	s_add_i32 s48, s19, 0x4000
	global_load_lds_dwordx4 v130, s[22:23]
	s_mov_b32 m0, s48
	s_add_i32 s49, s19, 0x6000
	global_load_lds_dwordx4 v134, s[4:5]
	s_mov_b32 m0, s49
	v_mov_b32_e32 v133, 0
	global_load_lds_dwordx4 v130, s[4:5]
	v_mov_b32_e32 v129, v133
	v_mov_b32_e32 v135, v133
	v_mov_b32_e32 v131, v133
	s_cmp_eq_u32 s8, 1
	s_mov_b32 s50, 0
	v_lshl_add_u64 v[6:7], s[24:25], 0, v[132:133]
	v_lshl_add_u64 v[4:5], s[24:25], 0, v[128:129]
	v_lshl_add_u64 v[0:1], s[22:23], 0, v[134:135]
	s_cselect_b64 s[4:5], -1, 0
	s_cmp_lg_u32 s8, 1
	v_lshl_add_u64 v[2:3], s[22:23], 0, v[130:131]
	s_cbranch_scc1 .LBB0_873
	s_barrier
	s_setprio 1

.LBB0_936:
	s_setprio 0
	s_cmp_lt_i32 s58, 8
	s_cselect_b64 s[2:3], -1, 0
	s_and_b64 s[6:7], s[2:3], s[0:1]
	s_andn2_b64 vcc, exec, s[6:7]
	s_cbranch_vccnz .LBB0_983
	s_cmpk_lt_i32 s30, 0x200
	s_cselect_b64 s[0:1], -1, 0
	s_cmpk_gt_i32 s30, 0x1ff
	v_readfirstlane_b32 s4, v196
	s_cbranch_scc1 .LBB0_943
	s_ashr_i32 s2, s30, 31
	s_lshr_b32 s2, s2, 29
	s_add_i32 s5, s30, s2
	s_and_b32 s2, s5, -8
	s_sub_i32 s8, s30, s2
	s_cmp_gt_i32 s8, -1
	s_cbranch_scc0 .LBB0_940
	s_lshl_b32 s9, s8, 6
	s_cbranch_execz .LBB0_941
	s_branch .LBB0_942

.LBB0_943:
	s_andn2_b64 vcc, exec, s[0:1]
	s_cbranch_vccnz .LBB0_983
	v_lshrrev_b32_e32 v3, 1, v196
	v_lshrrev_b32_e32 v4, 5, v196
	v_and_b32_e32 v3, 24, v3
	v_and_b32_e32 v4, 4, v4
	v_bfe_u32 v5, v196, 2, 2
	v_lshlrev_b32_e32 v0, 4, v196
	s_waitcnt lgkmcnt(0)
	v_and_b32_e32 v1, 32, v196
	v_bfe_u32 v2, v196, 2, 4
	v_or3_b32 v3, v4, v5, v3
	v_lshrrev_b32_e32 v4, 3, v196
	s_movk_i32 s0, 0x70
	v_bitop3_b32 v8, v0, v1, 48 bitop3:0x6c
	v_and_or_b32 v5, v4, s0, v2
	s_movk_i32 s0, 0x60
	v_add_u32_e32 v0, 0x2000, v0
	s_add_u32 s26, s56, 0x2380000
	v_and_or_b32 v4, v4, s0, v3
	v_lshrrev_b32_e32 v0, 7, v0
	s_movk_i32 s0, 0xf0
	s_addc_u32 s27, s57, 0
	s_lshr_b32 s1, s4, 6
	v_and_b32_e32 v9, 64, v196
	v_and_or_b32 v2, v0, s0, v2
	s_movk_i32 s0, 0xe0
	v_or_b32_e32 v1, v8, v9
	v_and_or_b32 v0, v0, s0, v3
	s_lshr_b32 s0, s4, 8
	s_lshl_b32 s28, s1, 10
	s_mul_i32 s3, s8, 0x160000
	v_lshrrev_b32_e32 v1, 1, v1
	v_mul_u32_u24_e32 v4, 0xb00, v4
	s_mul_hi_i32 s2, s8, 0x160000
	s_add_u32 s22, s26, s3
	v_or_b32_e32 v4, v4, v1
	s_addc_u32 s23, s27, s2
	s_add_i32 s29, s28, 0
	v_lshlrev_b32_e32 v154, 1, v4
	v_mul_u32_u24_e32 v0, 0xb00, v0
	s_add_i32 m0, s29, 0x10000
	v_or_b32_e32 v0, v0, v1
	global_load_lds_dwordx4 v154, s[22:23]
	s_add_i32 m0, s29, 0x12000
	v_lshlrev_b32_e32 v158, 1, v0
	s_add_u32 s2, s22, 0xb0000
	global_load_lds_dwordx4 v158, s[22:23]
	s_addc_u32 s3, s23, 0
	s_add_i32 m0, s29, 0x14000
	s_mul_i32 s9, s69, 0x160000
	global_load_lds_dwordx4 v154, s[2:3]
	s_add_i32 m0, s29, 0x16000
	v_mul_u32_u24_e32 v10, 0xb00, v5
	s_mul_hi_i32 s5, s69, 0x160000
	s_add_u32 s18, s36, s9
	v_or_b32_e32 v5, v1, v10
	v_mul_u32_u24_e32 v11, 0xb00, v2
	s_addc_u32 s19, s37, s5
	s_add_i32 s44, s29, 0x2000
	v_lshlrev_b32_e32 v152, 1, v5
	v_or_b32_e32 v2, v11, v1
	global_load_lds_dwordx4 v158, s[2:3]
	s_mov_b32 m0, s29
	s_add_u32 s2, s18, 0xb0000
	v_lshlrev_b32_e32 v156, 1, v2
	global_load_lds_dwordx4 v152, s[18:19]
	s_mov_b32 m0, s44
	s_addc_u32 s3, s19, 0
	s_add_i32 s45, s29, 0x4000
	global_load_lds_dwordx4 v156, s[18:19]
	s_mov_b32 m0, s45
	s_add_i32 s46, s29, 0x6000
	global_load_lds_dwordx4 v152, s[2:3]
	s_mov_b32 m0, s46
	v_mov_b32_e32 v155, 0
	global_load_lds_dwordx4 v156, s[2:3]
	v_mov_b32_e32 v159, v155
	v_mov_b32_e32 v153, v155
	v_mov_b32_e32 v157, v155
	s_cmp_eq_u32 s0, 1
	s_mov_b32 s9, 0
	v_lshl_add_u64 v[6:7], s[22:23], 0, v[154:155]
	v_lshl_add_u64 v[4:5], s[22:23], 0, v[158:159]
	v_lshl_add_u64 v[0:1], s[18:19], 0, v[152:153]
	s_cselect_b64 s[10:11], -1, 0
	s_cmp_lg_u32 s0, 1
	v_lshl_add_u64 v[2:3], s[18:19], 0, v[156:157]
	s_cbranch_scc1 .LBB0_946
	s_barrier
	s_setprio 1

.LBB0_1033:
	s_setprio 0
	s_cmp_lt_i32 s58, 9
	s_cselect_b64 s[2:3], -1, 0
	s_add_u32 s6, s56, 0x200000
	s_addc_u32 s7, s57, 0
	s_and_b64 s[8:9], s[2:3], s[0:1]
	s_andn2_b64 vcc, exec, s[8:9]
	s_cbranch_vccnz .LBB0_1364
	s_cmpk_lt_i32 s30, 0x400
	s_cselect_b64 s[0:1], -1, 0
	s_cmpk_gt_i32 s30, 0x3ff
	v_readfirstlane_b32 s16, v196
	s_cbranch_scc1 .LBB0_1040
	s_ashr_i32 s2, s30, 31
	s_lshr_b32 s2, s2, 29
	s_add_i32 s4, s30, s2
	s_and_b32 s2, s4, -8
	s_sub_i32 s5, s30, s2
	s_cmp_gt_i32 s5, -1
	s_cbranch_scc0 .LBB0_1037
	s_lshl_b32 s10, s5, 7
	s_cbranch_execz .LBB0_1038
	s_branch .LBB0_1039

.LBB0_1040:
	v_lshrrev_b32_e32 v2, 1, v196
	v_lshrrev_b32_e32 v3, 5, v196
	v_and_b32_e32 v2, 24, v2
	v_and_b32_e32 v3, 4, v3
	v_bfe_u32 v4, v196, 2, 2
	v_lshlrev_b32_e32 v0, 4, v196
	s_waitcnt lgkmcnt(0)
	v_and_b32_e32 v1, 32, v196
	v_bfe_u32 v215, v196, 2, 4
	v_or3_b32 v2, v3, v4, v2
	v_lshrrev_b32_e32 v3, 3, v196
	s_movk_i32 s2, 0x70
	v_bitop3_b32 v197, v0, v1, 48 bitop3:0x6c
	v_and_b32_e32 v214, 64, v196
	v_and_or_b32 v4, v3, s2, v215
	s_movk_i32 s2, 0x60
	v_add_u32_e32 v216, 0x2000, v0
	v_or_b32_e32 v1, v197, v214
	v_and_or_b32 v3, v3, s2, v2
	v_lshrrev_b32_e32 v0, 7, v216
	s_movk_i32 s2, 0xf0
	s_waitcnt vmcnt(23)
	v_lshl_or_b32 v162, v3, 11, v1
	v_and_or_b32 v3, v0, s2, v215
	s_movk_i32 s2, 0xe0
	v_and_or_b32 v0, v0, s2, v2
	v_lshl_or_b32 v160, v4, 11, v1
	s_waitcnt vmcnt(22)
	v_lshl_or_b32 v164, v3, 11, v1
	v_lshl_or_b32 v166, v0, 11, v1
	v_bfe_u32 v220, v196, 4, 2
	v_lshlrev_b32_e32 v0, 6, v196
	v_lshlrev_b32_e32 v1, 2, v196
	s_waitcnt vmcnt(21)
	v_lshlrev_b32_e32 v168, 4, v220
	v_and_b32_e32 v0, 0x3c0, v0
	v_and_b32_e32 v1, 32, v1
	v_and_b32_e32 v218, 15, v196
	v_lshlrev_b32_e32 v217, 3, v220
	s_andn2_b64 vcc, exec, s[0:1]
	v_bitop3_b32 v219, v168, v1, v0 bitop3:0x36
	s_cbranch_vccnz .LBB0_1348
	s_add_u32 s66, s56, 0x5200000
	s_addc_u32 s67, s57, 0
	s_lshr_b32 s0, s16, 6
	s_ashr_i32 s45, s44, 31
	s_ashr_i32 s51, s50, 31
	s_lshr_b32 s68, s16, 8
	s_lshl_b32 s69, s0, 10
	s_lshl_b64 s[2:3], s[44:45], 19
	s_lshl_b64 s[4:5], s[50:51], 19
	s_add_u32 s46, s66, s4
	s_addc_u32 s47, s67, s5
	s_add_i32 s70, s69, 0
	s_add_i32 m0, s70, 0x10000
	v_mov_b32_e32 v171, 0
	global_load_lds_dwordx4 v162, s[46:47]
	s_add_i32 m0, s70, 0x12000
	s_add_u32 s4, s46, 0x40000
	global_load_lds_dwordx4 v166, s[46:47]
	s_addc_u32 s5, s47, 0
	s_add_i32 m0, s70, 0x14000
	v_mov_b32_e32 v163, v171
	global_load_lds_dwordx4 v162, s[4:5]
	s_add_i32 m0, s70, 0x16000
	v_mov_b32_e32 v167, v171
	global_load_lds_dwordx4 v166, s[4:5]
	s_add_u32 s4, s60, s2
	s_addc_u32 s5, s61, s3
	s_add_i32 s71, s70, 0x2000
	s_mov_b32 m0, s70
	s_add_u32 s2, s4, 0x40000
	global_load_lds_dwordx4 v160, s[4:5]
	s_mov_b32 m0, s71
	s_addc_u32 s3, s5, 0
	s_add_i32 s72, s70, 0x4000
	global_load_lds_dwordx4 v164, s[4:5]
	s_mov_b32 m0, s72
	s_add_i32 s73, s70, 0x6000
	global_load_lds_dwordx4 v160, s[2:3]
	s_mov_b32 m0, s73
	v_mov_b32_e32 v161, v171
	global_load_lds_dwordx4 v164, s[2:3]
	v_mov_b32_e32 v165, v171
	s_cmp_eq_u32 s68, 1
	s_mov_b32 s74, 0
	v_lshl_add_u64 v[6:7], s[46:47], 0, v[162:163]
	v_lshl_add_u64 v[4:5], s[46:47], 0, v[166:167]
	v_lshl_add_u64 v[0:1], s[4:5], 0, v[160:161]
	s_cselect_b64 s[10:11], -1, 0
	s_cmp_lg_u32 s68, 1
	v_lshl_add_u64 v[2:3], s[4:5], 0, v[164:165]
	s_cbranch_scc1 .LBB0_1043
	s_barrier
	s_setprio 1

.LBB0_1348:
	s_cmpk_gt_i32 s30, 0xaff
	v_readfirstlane_b32 s1, v196
	s_cbranch_scc1 .LBB0_1364
	s_add_u32 s44, s56, 0x2900000
	s_addc_u32 s45, s57, 0
	s_ashr_i32 s47, s30, 31
	s_lshr_b32 s0, s47, 29
	s_add_i32 s0, s30, s0
	s_lshr_b32 s4, s1, 6
	s_ashr_i32 s2, s0, 3
	s_and_b32 s0, s0, -8
	s_lshr_b32 s10, s1, 8
	s_lshl_b32 s46, s4, 10
	s_sub_i32 s0, s30, s0
	s_cmp_lt_i32 s0, 0
	s_movk_i32 s48, 0x161
	s_cselect_b32 s3, s48, 0x160
	s_mul_i32 s0, s0, s3
	s_add_i32 s0, s0, s2
	s_mul_hi_i32 s2, s0, 0x2e8ba2e9
	s_lshr_b32 s3, s2, 31
	s_ashr_i32 s2, s2, 5
	s_add_i32 s2, s2, s3
	s_lshl_b32 s3, s2, 3
	s_mulk_i32 s2, 0xb0
	s_sub_i32 s2, s0, s2
	s_sext_i32_i16 s0, s2
	s_bfe_u32 s0, s0, 0x3001c
	s_add_i32 s5, s2, s0
	s_sext_i32_i16 s0, s5
	s_and_b32 s5, s5, 0xfff8
	s_sub_i32 s2, s2, s5
	s_sext_i32_i16 s2, s2
	s_lshr_b32 s0, s0, 3
	s_add_i32 s22, s3, s2
	s_ashr_i32 s23, s22, 31
	s_bfe_i64 s[12:13], s[0:1], 0x100000
	s_lshl_b64 s[2:3], s[22:23], 19
	s_lshl_b64 s[12:13], s[12:13], 19
	s_add_u32 s26, s44, s12
	s_addc_u32 s27, s45, s13
	s_add_i32 s23, s46, 0
	s_add_i32 m0, s23, 0x10000
	v_mov_b32_e32 v163, 0
	global_load_lds_dwordx4 v162, s[26:27]
	s_add_i32 m0, s23, 0x12000
	s_add_u32 s12, s26, 0x40000
	global_load_lds_dwordx4 v166, s[26:27]
	s_addc_u32 s13, s27, 0
	s_add_i32 m0, s23, 0x14000
	v_mov_b32_e32 v167, v163
	global_load_lds_dwordx4 v162, s[12:13]
	s_add_i32 m0, s23, 0x16000
	s_add_u32 s24, s60, s2
	s_addc_u32 s25, s61, s3
	s_add_i32 s49, s23, 0x2000
	global_load_lds_dwordx4 v166, s[12:13]
	s_mov_b32 m0, s23
	s_add_u32 s2, s24, 0x40000
	global_load_lds_dwordx4 v160, s[24:25]
	s_mov_b32 m0, s49
	s_addc_u32 s3, s25, 0
	s_add_i32 s50, s23, 0x4000
	global_load_lds_dwordx4 v164, s[24:25]
	s_mov_b32 m0, s50
	s_add_i32 s51, s23, 0x6000
	global_load_lds_dwordx4 v160, s[2:3]
	s_mov_b32 m0, s51
	v_mov_b32_e32 v161, v163
	global_load_lds_dwordx4 v164, s[2:3]
	v_mov_b32_e32 v165, v163
	s_cmp_eq_u32 s10, 1
	s_mov_b32 s64, 0
	s_waitcnt lgkmcnt(0)
	v_lshl_add_u64 v[6:7], s[26:27], 0, v[162:163]
	v_lshl_add_u64 v[4:5], s[26:27], 0, v[166:167]
	v_lshl_add_u64 v[0:1], s[24:25], 0, v[160:161]
	s_cselect_b64 s[2:3], -1, 0
	s_cmp_lg_u32 s10, 1
	v_lshl_add_u64 v[2:3], s[24:25], 0, v[164:165]
	s_cbranch_scc1 .LBB0_1351
	s_barrier
	s_setprio 1

.LBB0_1414:
	s_setprio 0
	s_cmp_lt_i32 s58, 10
	s_cselect_b64 s[2:3], -1, 0
	s_and_b64 s[8:9], s[2:3], s[0:1]
	s_andn2_b64 vcc, exec, s[8:9]
	s_cbranch_vccnz .LBB0_1461
	s_cmpk_lt_i32 s30, 0x200
	s_cselect_b64 s[0:1], -1, 0
	s_cmpk_gt_i32 s30, 0x1ff
	v_readfirstlane_b32 s4, v196
	s_cbranch_scc1 .LBB0_1421
	s_ashr_i32 s2, s30, 31
	s_lshr_b32 s2, s2, 29
	s_add_i32 s5, s30, s2
	s_and_b32 s2, s5, -8
	s_sub_i32 s10, s30, s2
	s_cmp_gt_i32 s10, -1
	s_cbranch_scc0 .LBB0_1418
	s_lshl_b32 s11, s10, 6
	s_cbranch_execz .LBB0_1419
	s_branch .LBB0_1420

.LBB0_1421:
	s_andn2_b64 vcc, exec, s[0:1]
	s_cbranch_vccnz .LBB0_1461
	s_waitcnt lgkmcnt(0)
	v_lshrrev_b32_e32 v3, 1, v196
	v_lshrrev_b32_e32 v4, 5, v196
	v_and_b32_e32 v3, 24, v3
	v_and_b32_e32 v4, 4, v4
	v_bfe_u32 v5, v196, 2, 2
	v_lshlrev_b32_e32 v0, 4, v196
	v_and_b32_e32 v1, 32, v196
	v_bfe_u32 v2, v196, 2, 4
	v_or3_b32 v3, v4, v5, v3
	v_lshrrev_b32_e32 v4, 3, v196
	s_movk_i32 s0, 0x70
	v_bitop3_b32 v8, v0, v1, 48 bitop3:0x6c
	v_and_or_b32 v5, v4, s0, v2
	s_movk_i32 s0, 0x60
	v_add_u32_e32 v0, 0x2000, v0
	s_add_u32 s28, s56, 0x3400000
	v_and_or_b32 v4, v4, s0, v3
	v_lshrrev_b32_e32 v0, 7, v0
	s_movk_i32 s0, 0xf0
	s_addc_u32 s29, s57, 0
	s_lshr_b32 s1, s4, 6
	v_and_b32_e32 v9, 64, v196
	v_and_or_b32 v2, v0, s0, v2
	s_movk_i32 s0, 0xe0
	v_or_b32_e32 v1, v8, v9
	v_and_or_b32 v0, v0, s0, v3
	s_lshr_b32 s0, s4, 8
	s_lshl_b32 s44, s1, 10
	s_mul_i32 s3, s10, 0x160000
	v_lshrrev_b32_e32 v1, 1, v1
	v_mul_u32_u24_e32 v4, 0xb00, v4
	s_mul_hi_i32 s2, s10, 0x160000
	s_add_u32 s24, s28, s3
	v_or_b32_e32 v4, v4, v1
	s_addc_u32 s25, s29, s2
	s_add_i32 s45, s44, 0
	v_lshlrev_b32_e32 v154, 1, v4
	v_mul_u32_u24_e32 v0, 0xb00, v0
	s_add_i32 m0, s45, 0x10000
	v_or_b32_e32 v0, v0, v1
	global_load_lds_dwordx4 v154, s[24:25]
	s_add_i32 m0, s45, 0x12000
	v_lshlrev_b32_e32 v158, 1, v0
	s_add_u32 s2, s24, 0xb0000
	global_load_lds_dwordx4 v158, s[24:25]
	s_addc_u32 s3, s25, 0
	s_add_i32 m0, s45, 0x14000
	s_mul_i32 s11, s71, 0x160000
	global_load_lds_dwordx4 v154, s[2:3]
	s_add_i32 m0, s45, 0x16000
	v_mul_u32_u24_e32 v10, 0xb00, v5
	s_mul_hi_i32 s5, s71, 0x160000
	s_add_u32 s22, s36, s11
	v_or_b32_e32 v5, v1, v10
	v_mul_u32_u24_e32 v11, 0xb00, v2
	s_addc_u32 s23, s37, s5
	s_add_i32 s46, s45, 0x2000
	v_lshlrev_b32_e32 v152, 1, v5
	v_or_b32_e32 v2, v11, v1
	global_load_lds_dwordx4 v158, s[2:3]
	s_mov_b32 m0, s45
	s_add_u32 s2, s22, 0xb0000
	v_lshlrev_b32_e32 v156, 1, v2
	global_load_lds_dwordx4 v152, s[22:23]
	s_mov_b32 m0, s46
	s_addc_u32 s3, s23, 0
	s_add_i32 s47, s45, 0x4000
	global_load_lds_dwordx4 v156, s[22:23]
	s_mov_b32 m0, s47
	s_add_i32 s48, s45, 0x6000
	global_load_lds_dwordx4 v152, s[2:3]
	s_mov_b32 m0, s48
	v_mov_b32_e32 v155, 0
	global_load_lds_dwordx4 v156, s[2:3]
	v_mov_b32_e32 v159, v155
	v_mov_b32_e32 v153, v155
	v_mov_b32_e32 v157, v155
	s_cmp_eq_u32 s0, 1
	s_mov_b32 s11, 0
	v_lshl_add_u64 v[6:7], s[24:25], 0, v[154:155]
	v_lshl_add_u64 v[4:5], s[24:25], 0, v[158:159]
	v_lshl_add_u64 v[0:1], s[22:23], 0, v[152:153]
	s_cselect_b64 s[12:13], -1, 0
	s_cmp_lg_u32 s0, 1
	v_lshl_add_u64 v[2:3], s[22:23], 0, v[156:157]
	s_cbranch_scc1 .LBB0_1424
	s_barrier
	s_setprio 1

.LBB0_1511:
	s_setprio 0
	s_cmp_lt_i32 s58, 11
	s_cselect_b64 s[2:3], -1, 0
	s_and_b64 s[8:9], s[2:3], s[0:1]
	s_andn2_b64 vcc, exec, s[8:9]
	s_cbranch_vccnz .LBB0_1819
	v_lshl_add_u32 v0, s30, 9, v196
	s_mov_b32 s0, 0x20000
	v_cmp_gt_i32_e32 vcc, s0, v0
	s_and_saveexec_b64 s[0:1], vcc
	s_cbranch_execz .LBB0_1515
	s_lshl_b32 s2, s31, 9
	s_waitcnt lgkmcnt(0)
	v_ashrrev_i32_e32 v1, 31, v0
	v_lshl_add_u64 v[2:3], v[0:1], 2, s[56:57]
	s_mov_b64 s[4:5], 0x300000
	s_ashr_i32 s3, s2, 31
	v_lshl_add_u64 v[2:3], v[2:3], 0, s[4:5]
	s_lshl_b64 s[4:5], s[2:3], 2
	s_mov_b64 s[10:11], 0
	v_mov_b32_e32 v5, 0
	s_mov_b32 s3, 0x1ffff

.LBB0_1521:
	s_andn2_b64 vcc, exec, s[0:1]
	s_cbranch_vccnz .LBB0_1819
	s_waitcnt lgkmcnt(0)
	v_lshrrev_b32_e32 v2, 1, v196
	v_lshrrev_b32_e32 v3, 5, v196
	v_and_b32_e32 v2, 24, v2
	v_and_b32_e32 v3, 4, v3
	v_bfe_u32 v4, v196, 2, 2
	v_lshlrev_b32_e32 v0, 4, v196
	v_and_b32_e32 v1, 32, v196
	v_bfe_u32 v10, v196, 2, 4
	v_or3_b32 v2, v3, v4, v2
	v_lshrrev_b32_e32 v3, 3, v196
	s_movk_i32 s1, 0x70
	v_bitop3_b32 v8, v0, v1, 48 bitop3:0x6c
	v_and_b32_e32 v9, 64, v196
	v_and_or_b32 v4, v3, s1, v10
	s_movk_i32 s1, 0x60
	v_add_u32_e32 v11, 0x2000, v0
	s_add_u32 s46, s56, 0x5600000
	v_or_b32_e32 v1, v8, v9
	v_and_or_b32 v3, v3, s1, v2
	v_lshrrev_b32_e32 v0, 7, v11
	s_movk_i32 s1, 0xf0
	s_addc_u32 s47, s57, 0
	s_lshr_b32 s0, s14, 6
	s_waitcnt vmcnt(0)
	v_lshl_or_b32 v162, v3, 11, v1
	v_and_or_b32 v3, v0, s1, v10
	s_movk_i32 s1, 0xe0
	s_ashr_i32 s3, s2, 31
	s_ashr_i32 s27, s26, 31
	v_and_or_b32 v0, v0, s1, v2
	s_lshr_b32 s1, s14, 8
	s_lshl_b32 s48, s0, 10
	s_lshl_b64 s[4:5], s[2:3], 19
	s_lshl_b64 s[6:7], s[26:27], 19
	s_add_u32 s28, s46, s6
	s_addc_u32 s29, s47, s7
	s_add_i32 s49, s48, 0
	s_add_i32 m0, s49, 0x10000
	v_lshl_or_b32 v166, v0, 11, v1
	global_load_lds_dwordx4 v162, s[28:29]
	s_add_i32 m0, s49, 0x12000
	s_add_u32 s6, s28, 0x40000
	global_load_lds_dwordx4 v166, s[28:29]
	s_addc_u32 s7, s29, 0
	s_add_i32 m0, s49, 0x14000
	v_lshl_or_b32 v160, v4, 11, v1
	global_load_lds_dwordx4 v162, s[6:7]
	s_add_i32 m0, s49, 0x16000
	s_add_u32 s4, s60, s4
	s_addc_u32 s5, s61, s5
	s_add_i32 s50, s49, 0x2000
	global_load_lds_dwordx4 v166, s[6:7]
	s_mov_b32 m0, s49
	s_add_u32 s6, s4, 0x40000
	v_lshl_or_b32 v164, v3, 11, v1
	global_load_lds_dwordx4 v160, s[4:5]
	s_mov_b32 m0, s50
	s_addc_u32 s7, s5, 0
	s_add_i32 s51, s49, 0x4000
	global_load_lds_dwordx4 v164, s[4:5]
	s_mov_b32 m0, s51
	s_add_i32 s64, s49, 0x6000
	global_load_lds_dwordx4 v160, s[6:7]
	s_mov_b32 m0, s64
	v_mov_b32_e32 v169, 0
	global_load_lds_dwordx4 v164, s[6:7]
	v_mov_b32_e32 v163, v169
	v_mov_b32_e32 v167, v169
	v_mov_b32_e32 v161, v169
	v_mov_b32_e32 v165, v169
	s_cmp_eq_u32 s1, 1
	s_mov_b32 s65, 0
	v_lshl_add_u64 v[6:7], s[28:29], 0, v[162:163]
	v_lshl_add_u64 v[4:5], s[28:29], 0, v[166:167]
	v_lshl_add_u64 v[0:1], s[4:5], 0, v[160:161]
	s_cselect_b64 s[6:7], -1, 0
	s_cmp_lg_u32 s1, 1
	v_lshl_add_u64 v[2:3], s[4:5], 0, v[164:165]
	s_cbranch_scc1 .LBB0_1524
	s_barrier
	s_setprio 1

.LBB0_1869:
	s_setprio 0
	s_cmp_lt_i32 s58, 12
	s_cselect_b64 s[2:3], -1, 0
	s_and_b64 s[44:45], s[2:3], s[0:1]
	s_andn2_b64 vcc, exec, s[44:45]
	s_cbranch_vccnz .LBB0_1970
	s_cmpk_gt_i32 s33, 0x7ff
	v_readfirstlane_b32 s16, v196
	s_cbranch_scc1 .LBB0_1970
	v_lshrrev_b32_e32 v0, 5, v224
	s_waitcnt lgkmcnt(0)
	v_and_b32_e32 v2, 3, v196
	v_lshlrev_b32_e32 v4, 1, v196
	v_lshlrev_b32_e32 v227, 4, v2
	v_and_b32_e32 v5, 32, v4
	v_lshlrev_b32_e32 v6, 3, v2
	v_lshlrev_b32_e32 v2, 2, v0
	v_lshrrev_b32_e32 v4, 2, v196
	v_and_or_b32 v4, v4, 3, v2
	v_and_b32_e32 v197, 31, v196
	v_lshlrev_b32_e32 v228, 6, v4
	v_lshlrev_b32_e64 v4, v196, -1
	s_waitcnt vmcnt(0)
	v_lshlrev_b32_e32 v164, 4, v0
	v_not_b32_e32 v229, v4
	v_lshlrev_b32_e32 v4, 3, v0
	v_lshlrev_b32_e32 v0, 3, v196
	v_sub_u32_e32 v7, v197, v2
	s_movk_i32 s4, 0x81
	v_and_b32_e32 v230, 56, v0
	v_add_u32_e32 v8, -1, v7
	v_mov_b32_e32 v32, 0xff800000
	v_bfrev_b32_e32 v0, 1
	v_cmp_gt_u32_e32 vcc, s4, v7
	v_add_u32_e32 v9, -2, v7
	v_add_u32_e32 v10, -3, v7
	v_cndmask_b32_e32 v16, v32, v0, vcc
	v_cmp_gt_u32_e32 vcc, s4, v8
	v_add_u32_e32 v11, -8, v7
	v_add_u32_e32 v12, -9, v7
	v_cndmask_b32_e32 v17, v32, v0, vcc
	v_cmp_gt_u32_e32 vcc, s4, v9
	v_add_u32_e32 v13, -10, v7
	s_mul_i32 s1, s30, 0x30000
	v_cndmask_b32_e32 v18, v32, v0, vcc
	v_cmp_gt_u32_e32 vcc, s4, v10
	v_add_u32_e32 v14, -11, v7
	s_mul_hi_i32 s0, s30, 0x30000
	v_cndmask_b32_e32 v19, v32, v0, vcc
	v_cmp_gt_u32_e32 vcc, s4, v11
	s_add_u32 s18, s56, s1
	v_add_u32_e32 v15, -16, v7
	v_cndmask_b32_e32 v20, v32, v0, vcc
	v_cmp_gt_u32_e32 vcc, s4, v12
	s_addc_u32 s19, s57, s0
	s_mul_i32 s1, s30, 0xc00
	v_cndmask_b32_e32 v21, v32, v0, vcc
	v_cmp_gt_u32_e32 vcc, s4, v13
	v_subrev_u32_e32 v25, 17, v7
	s_mul_hi_i32 s0, s30, 0xc00
	v_cndmask_b32_e32 v22, v32, v0, vcc
	v_cmp_gt_u32_e32 vcc, s4, v14
	s_add_u32 s1, s56, s1
	v_subrev_u32_e32 v26, 18, v7
	v_cndmask_b32_e32 v23, v32, v0, vcc
	v_cmp_gt_u32_e32 vcc, s4, v15
	s_addc_u32 s0, s57, s0
	v_subrev_u32_e32 v27, 19, v7
	v_cndmask_b32_e32 v24, v32, v0, vcc
	v_cmp_gt_u32_e32 vcc, s4, v25
	s_add_u32 s46, s1, 0x140000
	v_subrev_u32_e32 v28, 24, v7
	v_cndmask_b32_e32 v25, v32, v0, vcc
	v_cmp_gt_u32_e32 vcc, s4, v26
	s_addc_u32 s47, s0, 0
	v_subrev_u32_e32 v29, 25, v7
	v_cndmask_b32_e32 v26, v32, v0, vcc
	v_cmp_gt_u32_e32 vcc, s4, v27
	s_add_u32 s48, s1, 0x600000
	v_subrev_u32_e32 v30, 26, v7
	v_cndmask_b32_e32 v27, v32, v0, vcc
	v_cmp_gt_u32_e32 vcc, s4, v28
	s_addc_u32 s49, s0, 0
	v_subrev_u32_e32 v31, 27, v7
	v_cndmask_b32_e32 v28, v32, v0, vcc
	v_cmp_gt_u32_e32 vcc, s4, v29
	s_lshr_b32 s82, s16, 6
	s_lshl_b32 s83, s82, 5
	v_cndmask_b32_e32 v29, v32, v0, vcc
	v_cmp_gt_u32_e32 vcc, s4, v30
	v_lshlrev_b32_e32 v1, 4, v196
	v_lshrrev_b32_e32 v225, 3, v224
	v_cndmask_b32_e32 v30, v32, v0, vcc
	v_cmp_gt_u32_e32 vcc, s4, v31
	s_mul_i32 s4, s82, 0x4600
	s_add_i32 s4, s4, 0
	s_cmp_lt_u32 s16, 64
	v_and_b32_e32 v226, 0x70, v1
	v_lshlrev_b32_e32 v1, 9, v196
	s_cselect_b64 s[64:65], -1, 0
	s_cmp_gt_u32 s16, 63
	v_and_b32_e32 v1, 0x800, v1
	v_lshlrev_b32_e32 v3, 6, v225
	s_movk_i32 s5, 0x90
	v_mov_b32_e32 v7, s4
	s_cselect_b64 s[66:67], -1, 0
	s_cmpk_gt_u32 s16, 0x7f
	v_mad_u32_u24 v231, v197, s5, v7
	v_mad_u32_u24 v232, v225, s5, v7
	v_add3_u32 v233, s4, v1, v3
	v_add3_u32 v234, s4, v5, v6
	s_cselect_b64 s[4:5], -1, 0
	s_cmpk_gt_u32 s16, 0xbf
	s_cselect_b64 s[6:7], -1, 0
	s_cmpk_gt_u32 s16, 0xff
	v_mov_b32_e32 v167, 0
	s_cselect_b64 s[8:9], -1, 0
	s_cmpk_gt_u32 s16, 0x13f
	v_mov_b32_e32 v165, v167
	s_cselect_b64 s[10:11], -1, 0
	s_cmpk_gt_u32 s16, 0x17f
	s_cselect_b64 s[12:13], -1, 0
	s_cmpk_gt_u32 s16, 0x1bf
	v_lshl_add_u64 v[6:7], s[18:19], 0, v[164:165]
	s_mov_b64 s[18:19], 0x1d000000
	v_and_b32_e32 v166, 32, v196
	s_cselect_b64 s[14:15], -1, 0
	s_cmpk_gt_u32 s16, 0x1ff
	v_lshl_add_u64 v[172:173], v[6:7], 0, s[18:19]
	v_lshl_add_u64 v[6:7], s[56:57], 0, v[166:167]
	s_mov_b64 s[18:19], 0x300080
	s_cselect_b64 s[16:17], -1, 0
	v_lshl_add_u64 v[174:175], v[6:7], 0, s[18:19]
	s_lshl_b32 s18, s82, 2
	v_lshlrev_b32_e32 v1, 8, v196
	v_or_b32_e32 v170, s83, v197
	s_add_i32 s86, s18, 0
	v_and_b32_e32 v166, 0x3800, v1
	v_writelane_b32 v254, s92, 0
	s_mov_b32 s51, 0
	v_cmp_ne_u32_e64 s[0:1], 0, v224
	v_cmp_gt_u32_e64 s[2:3], 32, v224
	v_lshl_add_u64 v[168:169], s[36:37], 0, v[164:165]
	v_cndmask_b32_e32 v31, v32, v0, vcc
	v_or_b32_e32 v235, s83, v225
	v_mov_b32_e32 v171, v167
	v_or_b32_e32 v236, 0x100, v170
	v_or_b32_e32 v237, 0x200, v170
	s_lshl_b32 s84, s33, 2
	s_lshl_b32 s85, s31, 2
	s_add_i32 s86, s86, 0x23000
	v_lshl_add_u64 v[176:177], s[56:57], 0, v[166:167]
	v_lshlrev_b32_e32 v178, 1, v4
	s_add_i32 s87, 0, 0x23200
	s_mov_b32 s88, 0x40c00000
	s_mov_b64 s[68:69], 0x80000
	v_lshlrev_b32_e32 v180, 1, v2
	v_mov_b32_e32 v165, 0x100
	v_mov_b32_e32 v238, 0x10000
	v_mov_b32_e32 v239, -1
	s_mov_b32 s89, 0
	s_mov_b32 s90, s33
	v_writelane_b32 v254, s93, 1
	s_branch .LBB0_1873

.LBB0_2020:
	s_setprio 0
	s_cmp_lt_i32 s58, 13
	s_cselect_b64 s[2:3], -1, 0
	s_and_b64 s[4:5], s[2:3], s[0:1]
	s_andn2_b64 vcc, exec, s[4:5]
	s_cbranch_vccnz .LBB0_2063
	s_cmpk_lt_i32 s30, 0x200
	s_cselect_b64 s[0:1], -1, 0
	s_cmpk_gt_i32 s30, 0x1ff
	v_readfirstlane_b32 s12, v196
	s_cbranch_scc1 .LBB0_2027
	s_ashr_i32 s2, s30, 31
	s_lshr_b32 s2, s2, 29
	s_add_i32 s6, s30, s2
	s_and_b32 s2, s6, -8
	s_sub_i32 s7, s30, s2
	s_cmp_gt_i32 s7, -1
	s_cbranch_scc0 .LBB0_2024
	s_lshl_b32 s8, s7, 6
	s_cbranch_execz .LBB0_2025
	s_branch .LBB0_2026

.LBB0_2027:
	s_andn2_b64 vcc, exec, s[0:1]
	s_cbranch_vccnz .LBB0_2063
	s_waitcnt lgkmcnt(0)
	v_lshrrev_b32_e32 v2, 1, v196
	v_lshrrev_b32_e32 v3, 5, v196
	v_and_b32_e32 v2, 24, v2
	v_and_b32_e32 v3, 4, v3
	v_bfe_u32 v4, v196, 2, 2
	v_lshlrev_b32_e32 v0, 4, v196
	v_and_b32_e32 v1, 32, v196
	v_bfe_u32 v10, v196, 2, 4
	v_or3_b32 v2, v3, v4, v2
	v_lshrrev_b32_e32 v3, 3, v196
	s_movk_i32 s0, 0x70
	v_bitop3_b32 v8, v0, v1, 48 bitop3:0x6c
	v_and_b32_e32 v9, 64, v196
	v_and_or_b32 v4, v3, s0, v10
	s_movk_i32 s0, 0x60
	v_add_u32_e32 v11, 0x2000, v0
	s_add_u32 s40, s56, 0x5800000
	v_or_b32_e32 v1, v8, v9
	v_and_or_b32 v3, v3, s0, v2
	v_lshrrev_b32_e32 v0, 7, v11
	s_movk_i32 s0, 0xf0
	s_addc_u32 s41, s57, 0
	s_lshr_b32 s1, s12, 6
	v_lshl_or_b32 v154, v3, 11, v1
	v_and_or_b32 v3, v0, s0, v10
	s_movk_i32 s0, 0xe0
	s_ashr_i32 s23, s22, 31
	s_ashr_i32 s7, s6, 31
	v_and_or_b32 v0, v0, s0, v2
	s_lshr_b32 s0, s12, 8
	s_lshl_b32 s42, s1, 10
	s_lshl_b64 s[2:3], s[22:23], 19
	s_lshl_b64 s[8:9], s[6:7], 19
	s_add_u32 s26, s40, s8
	s_addc_u32 s27, s41, s9
	s_add_i32 s43, s42, 0
	s_add_i32 m0, s43, 0x10000
	v_lshl_or_b32 v158, v0, 11, v1
	global_load_lds_dwordx4 v154, s[26:27]
	s_add_i32 m0, s43, 0x12000
	s_add_u32 s8, s26, 0x40000
	global_load_lds_dwordx4 v158, s[26:27]
	s_addc_u32 s9, s27, 0
	s_add_i32 m0, s43, 0x14000
	v_lshl_or_b32 v152, v4, 11, v1
	global_load_lds_dwordx4 v154, s[8:9]
	s_add_i32 m0, s43, 0x16000
	s_add_u32 s24, s38, s2
	s_addc_u32 s25, s39, s3
	s_add_i32 s44, s43, 0x2000
	global_load_lds_dwordx4 v158, s[8:9]
	s_mov_b32 m0, s43
	s_add_u32 s2, s24, 0x40000
	v_lshl_or_b32 v156, v3, 11, v1
	global_load_lds_dwordx4 v152, s[24:25]
	s_mov_b32 m0, s44
	s_addc_u32 s3, s25, 0
	s_add_i32 s45, s43, 0x4000
	global_load_lds_dwordx4 v156, s[24:25]
	s_mov_b32 m0, s45
	s_add_i32 s46, s43, 0x6000
	global_load_lds_dwordx4 v152, s[2:3]
	s_mov_b32 m0, s46
	v_mov_b32_e32 v155, 0
	global_load_lds_dwordx4 v156, s[2:3]
	v_mov_b32_e32 v159, v155
	v_mov_b32_e32 v153, v155
	v_mov_b32_e32 v157, v155
	s_cmp_eq_u32 s0, 1
	s_mov_b32 s7, 0
	v_lshl_add_u64 v[6:7], s[26:27], 0, v[154:155]
	v_lshl_add_u64 v[4:5], s[26:27], 0, v[158:159]
	v_lshl_add_u64 v[0:1], s[24:25], 0, v[152:153]
	s_cselect_b64 s[8:9], -1, 0
	s_cmp_lg_u32 s0, 1
	v_lshl_add_u64 v[2:3], s[24:25], 0, v[156:157]
	s_cbranch_scc1 .LBB0_2030
	s_barrier
	s_setprio 1

.LBB0_2113:
	s_setprio 0
	s_cmp_lt_i32 s58, 14
	s_cselect_b64 s[2:3], -1, 0
	s_and_b64 s[2:3], s[2:3], s[0:1]
	s_andn2_b64 vcc, exec, s[2:3]
	s_cbranch_vccnz .LBB0_2130
	s_cmpk_gt_i32 s30, 0xaff
	v_readfirstlane_b32 s1, v196
	s_cbranch_scc1 .LBB0_2130
	v_lshrrev_b32_e32 v0, 5, v196
	s_waitcnt lgkmcnt(0)
	v_lshrrev_b32_e32 v2, 1, v196
	v_and_b32_e32 v0, 4, v0
	v_bfe_u32 v1, v196, 2, 2
	v_and_b32_e32 v2, 24, v2
	v_or3_b32 v0, v0, v1, v2
	v_lshlrev_b32_e32 v1, 4, v196
	v_add_u32_e32 v8, 0x2000, v1
	v_lshrrev_b32_e32 v2, 7, v8
	s_movk_i32 s0, 0xe0
	v_and_b32_e32 v4, 32, v196
	v_and_or_b32 v3, v2, s0, v0
	v_bitop3_b32 v9, v1, v4, 48 bitop3:0x6c
	v_and_b32_e32 v10, 64, v196
	v_bfe_u32 v11, v196, 2, 4
	s_movk_i32 s0, 0xf0
	v_or_b32_e32 v1, v9, v10
	v_and_or_b32 v2, v2, s0, v11
	s_add_u32 s26, s56, 0x3980000
	v_lshl_or_b32 v130, v2, 11, v1
	v_lshrrev_b32_e32 v2, 3, v196
	s_movk_i32 s0, 0x60
	s_addc_u32 s27, s57, 0
	v_and_or_b32 v0, v2, s0, v0
	s_movk_i32 s0, 0x70
	s_ashr_i32 s29, s30, 31
	v_lshl_or_b32 v132, v0, 11, v1
	v_and_or_b32 v0, v2, s0, v11
	s_lshr_b32 s0, s29, 29
	s_add_i32 s0, s30, s0
	s_lshr_b32 s6, s1, 6
	s_ashr_i32 s4, s0, 3
	s_and_b32 s0, s0, -8
	s_lshr_b32 s8, s1, 8
	s_lshl_b32 s28, s6, 10
	s_sub_i32 s0, s30, s0
	s_cmp_lt_i32 s0, 0
	s_movk_i32 s38, 0x161
	s_cselect_b32 s5, s38, 0x160
	s_mul_i32 s0, s0, s5
	s_add_i32 s0, s0, s4
	s_mul_hi_i32 s4, s0, 0x2e8ba2e9
	s_lshr_b32 s5, s4, 31
	s_ashr_i32 s4, s4, 5
	s_add_i32 s4, s4, s5
	s_lshl_b32 s5, s4, 3
	s_mulk_i32 s4, 0xb0
	s_sub_i32 s4, s0, s4
	s_sext_i32_i16 s0, s4
	s_bfe_u32 s0, s0, 0x3001c
	s_add_i32 s7, s4, s0
	s_sext_i32_i16 s0, s7
	s_and_b32 s7, s7, 0xfff8
	s_sub_i32 s4, s4, s7
	s_sext_i32_i16 s4, s4
	s_lshr_b32 s0, s0, 3
	s_add_i32 s18, s5, s4
	s_ashr_i32 s19, s18, 31
	s_bfe_i64 s[10:11], s[0:1], 0x100000
	s_lshl_b64 s[4:5], s[18:19], 19
	s_lshl_b64 s[10:11], s[10:11], 19
	s_add_u32 s22, s26, s10
	s_addc_u32 s23, s27, s11
	s_add_i32 s19, s28, 0
	s_add_i32 m0, s19, 0x10000
	v_lshl_or_b32 v128, v3, 11, v1
	global_load_lds_dwordx4 v132, s[22:23]
	s_add_i32 m0, s19, 0x12000
	s_add_u32 s10, s22, 0x40000
	global_load_lds_dwordx4 v128, s[22:23]
	s_addc_u32 s11, s23, 0
	s_add_i32 m0, s19, 0x14000
	v_lshl_or_b32 v134, v0, 11, v1
	global_load_lds_dwordx4 v132, s[10:11]
	s_add_i32 m0, s19, 0x16000
	s_add_u32 s20, s60, s4
	s_addc_u32 s21, s61, s5
	s_add_i32 s39, s19, 0x2000
	global_load_lds_dwordx4 v128, s[10:11]
	s_mov_b32 m0, s19
	s_add_u32 s4, s20, 0x40000
	global_load_lds_dwordx4 v134, s[20:21]
	s_mov_b32 m0, s39
	s_addc_u32 s5, s21, 0
	s_add_i32 s40, s19, 0x4000
	global_load_lds_dwordx4 v130, s[20:21]
	s_mov_b32 m0, s40
	s_add_i32 s41, s19, 0x6000
	global_load_lds_dwordx4 v134, s[4:5]
	s_mov_b32 m0, s41
	v_mov_b32_e32 v133, 0
	global_load_lds_dwordx4 v130, s[4:5]
	v_mov_b32_e32 v129, v133
	v_mov_b32_e32 v135, v133
	v_mov_b32_e32 v131, v133
	s_cmp_eq_u32 s8, 1
	s_mov_b32 s42, 0
	v_lshl_add_u64 v[6:7], s[22:23], 0, v[132:133]
	v_lshl_add_u64 v[4:5], s[22:23], 0, v[128:129]
	v_lshl_add_u64 v[0:1], s[20:21], 0, v[134:135]
	s_cselect_b64 s[4:5], -1, 0
	s_cmp_lg_u32 s8, 1
	v_lshl_add_u64 v[2:3], s[20:21], 0, v[130:131]
	s_cbranch_scc1 .LBB0_2117
	s_barrier
	s_setprio 1

.LBB0_2180:
	s_setprio 0
	s_cmp_lt_i32 s58, 15
	s_cselect_b64 s[2:3], -1, 0
	s_and_b64 s[6:7], s[2:3], s[0:1]
	s_andn2_b64 vcc, exec, s[6:7]
	s_cbranch_vccnz .LBB0_2227
	s_cmpk_lt_i32 s30, 0x200
	s_cselect_b64 s[0:1], -1, 0
	s_cmpk_gt_i32 s30, 0x1ff
	v_readfirstlane_b32 s4, v196
	s_cbranch_scc1 .LBB0_2187
	s_ashr_i32 s2, s30, 31
	s_lshr_b32 s2, s2, 29
	s_add_i32 s9, s30, s2
	s_and_b32 s2, s9, -8
	s_sub_i32 s5, s30, s2
	s_cmp_gt_i32 s5, -1
	s_cbranch_scc0 .LBB0_2184
	s_lshl_b32 s8, s5, 6
	s_ashr_i32 s2, s9, 3
	s_cbranch_execz .LBB0_2185
	s_branch .LBB0_2186

.LBB0_2187:
	s_andn2_b64 vcc, exec, s[0:1]
	s_cbranch_vccnz .LBB0_2227
	s_waitcnt lgkmcnt(0)
	v_lshrrev_b32_e32 v3, 1, v196
	v_lshrrev_b32_e32 v4, 5, v196
	v_and_b32_e32 v3, 24, v3
	v_and_b32_e32 v4, 4, v4
	v_bfe_u32 v5, v196, 2, 2
	v_lshlrev_b32_e32 v0, 4, v196
	v_and_b32_e32 v1, 32, v196
	v_bfe_u32 v2, v196, 2, 4
	v_or3_b32 v3, v4, v5, v3
	v_lshrrev_b32_e32 v4, 3, v196
	s_movk_i32 s0, 0x70
	v_bitop3_b32 v8, v0, v1, 48 bitop3:0x6c
	v_and_or_b32 v5, v4, s0, v2
	s_movk_i32 s0, 0x60
	v_add_u32_e32 v0, 0x2000, v0
	s_add_u32 s24, s56, 0x4480000
	v_and_or_b32 v4, v4, s0, v3
	v_lshrrev_b32_e32 v0, 7, v0
	s_movk_i32 s0, 0xf0
	s_addc_u32 s25, s57, 0
	s_lshr_b32 s1, s4, 6
	v_and_b32_e32 v9, 64, v196
	v_and_or_b32 v2, v0, s0, v2
	s_movk_i32 s0, 0xe0
	v_or_b32_e32 v1, v8, v9
	v_and_or_b32 v0, v0, s0, v3
	s_lshr_b32 s0, s4, 8
	s_lshl_b32 s26, s1, 10
	s_mul_i32 s3, s8, 0x160000
	v_lshrrev_b32_e32 v1, 1, v1
	v_mul_u32_u24_e32 v4, 0xb00, v4
	s_mul_hi_i32 s2, s8, 0x160000
	s_add_u32 s20, s24, s3
	v_or_b32_e32 v4, v4, v1
	s_addc_u32 s21, s25, s2
	s_add_i32 s27, s26, 0
	v_lshlrev_b32_e32 v154, 1, v4
	v_mul_u32_u24_e32 v0, 0xb00, v0
	s_add_i32 m0, s27, 0x10000
	v_or_b32_e32 v0, v0, v1
	global_load_lds_dwordx4 v154, s[20:21]
	s_add_i32 m0, s27, 0x12000
	v_lshlrev_b32_e32 v158, 1, v0
	s_add_u32 s2, s20, 0xb0000
	global_load_lds_dwordx4 v158, s[20:21]
	s_addc_u32 s3, s21, 0
	s_add_i32 m0, s27, 0x14000
	s_mul_i32 s9, s49, 0x160000
	global_load_lds_dwordx4 v154, s[2:3]
	s_add_i32 m0, s27, 0x16000
	v_mul_u32_u24_e32 v10, 0xb00, v5
	s_mul_hi_i32 s5, s49, 0x160000
	s_add_u32 s18, s36, s9
	v_or_b32_e32 v5, v1, v10
	v_mul_u32_u24_e32 v11, 0xb00, v2
	s_addc_u32 s19, s37, s5
	s_add_i32 s28, s27, 0x2000
	v_lshlrev_b32_e32 v152, 1, v5
	v_or_b32_e32 v2, v11, v1
	global_load_lds_dwordx4 v158, s[2:3]
	s_mov_b32 m0, s27
	s_add_u32 s2, s18, 0xb0000
	v_lshlrev_b32_e32 v156, 1, v2
	global_load_lds_dwordx4 v152, s[18:19]
	s_mov_b32 m0, s28
	s_addc_u32 s3, s19, 0
	s_add_i32 s29, s27, 0x4000
	global_load_lds_dwordx4 v156, s[18:19]
	s_mov_b32 m0, s29
	s_add_i32 s38, s27, 0x6000
	global_load_lds_dwordx4 v152, s[2:3]
	s_mov_b32 m0, s38
	v_mov_b32_e32 v155, 0
	global_load_lds_dwordx4 v156, s[2:3]
	v_mov_b32_e32 v159, v155
	v_mov_b32_e32 v153, v155
	v_mov_b32_e32 v157, v155
	s_cmp_eq_u32 s0, 1
	s_mov_b32 s9, 0
	v_lshl_add_u64 v[6:7], s[20:21], 0, v[154:155]
	v_lshl_add_u64 v[4:5], s[20:21], 0, v[158:159]
	v_lshl_add_u64 v[0:1], s[18:19], 0, v[152:153]
	s_cselect_b64 s[10:11], -1, 0
	s_cmp_lg_u32 s0, 1
	v_lshl_add_u64 v[2:3], s[18:19], 0, v[156:157]
	s_cbranch_scc1 .LBB0_2190
	s_barrier
	s_setprio 1

.LBB0_2277:
	s_setprio 0
	s_cmp_lt_i32 s58, 16
	s_cselect_b64 s[2:3], -1, 0
	s_and_b64 s[0:1], s[2:3], s[0:1]
	s_andn2_b64 vcc, exec, s[0:1]
	s_cbranch_vccnz .LBB0_2293
	s_lshl_b32 s0, s33, 3
	s_add_i32 s0, s0, s80
	s_cmpk_gt_i32 s0, 0x7fff
	s_cbranch_scc1 .LBB0_2293
	v_lshlrev_b32_e32 v52, 5, v224
	s_waitcnt lgkmcnt(0)
	global_load_dwordx4 v[0:3], v52, s[52:53] offset:16
	global_load_dwordx4 v[4:7], v52, s[52:53]
	global_load_dwordx4 v[8:11], v52, s[52:53] offset:2064
	global_load_dwordx4 v[12:15], v52, s[52:53] offset:2048
	s_mov_b32 s4, 0
	v_mov_b32_e32 v53, 0
	s_mov_b32 s6, s4
	s_mov_b32 s7, s4
	v_lshl_add_u64 v[54:55], s[54:55], 0, v[52:53]
	v_lshlrev_b32_e32 v52, 4, v224
	s_mov_b32 s5, s4
	v_mov_b64_e32 v[18:19], s[6:7]
	s_lshl_b32 s14, s31, 3
	v_lshl_add_u64 v[56:57], s[60:61], 0, v[52:53]
	s_lshl_b32 s15, s31, 5
	s_lshl_b32 s16, s31, 4
	s_mul_i32 s17, s31, 24
	v_mov_b64_e32 v[16:17], s[4:5]
	v_mov_b32_e32 v52, 0x358637bd
	s_branch .LBB0_2281
